# twiddle-table loads issued together; attention Q-fragment loads issued together (global instead of flat); band mask with one compare per element
# speedup vs baseline: 1.0123x; 1.0123x over previous
; #define LAS __attribute__((address_space(3)))
; __device__ __forceinline__ int otid() { int t = threadIdx.x; asm volatile("" : "+v"(t)); return t; }
; __device__ void phase_mix(const Params& p, int l, LAS unsigned char* lds) {
;     ...
;     { const int tid = otid(); const f32x2* TW = (const f32x2*)(p.ws + OFF_TW); LAS f32x2* tw = (LAS f32x2*)(lds + 65536);
;       for (int i = tid; i < 4095; i += 512) tw[i] = TW[i]; }
.LBB0_32:
	global_load_dwordx2 v[4:5], v[0:1], off
	v_lshl_add_u64 v[0:1], v[0:1], 0, s[10:11]
	global_load_dwordx2 v[6:7], v[0:1], off
	v_lshl_add_u64 v[0:1], v[0:1], 0, s[10:11]
	global_load_dwordx2 v[8:9], v[0:1], off
	v_lshl_add_u64 v[0:1], v[0:1], 0, s[10:11]
	global_load_dwordx2 v[10:11], v[0:1], off
	v_lshl_add_u64 v[0:1], v[0:1], 0, s[10:11]
	global_load_dwordx2 v[12:13], v[0:1], off
	v_lshl_add_u64 v[0:1], v[0:1], 0, s[10:11]
	global_load_dwordx2 v[14:15], v[0:1], off
	v_lshl_add_u64 v[0:1], v[0:1], 0, s[10:11]
	global_load_dwordx2 v[16:17], v[0:1], off
	v_lshl_add_u64 v[0:1], v[0:1], 0, s[10:11]
	global_load_dwordx2 v[18:19], v[0:1], off
	s_waitcnt vmcnt(0)
	ds_write_b64 v3, v[4:5]
	ds_write_b64 v3, v[6:7] offset:4096
	ds_write_b64 v3, v[8:9] offset:8192
	ds_write_b64 v3, v[10:11] offset:12288
	ds_write_b64 v3, v[12:13] offset:16384
	ds_write_b64 v3, v[14:15] offset:20480
	ds_write_b64 v3, v[16:17] offset:24576
	ds_write_b64 v3, v[18:19] offset:28672

; #define LAS __attribute__((address_space(3)))
; __device__ __forceinline__ unsigned pk2(float lo, float hi) { unsigned r; asm volatile("v_cvt_pk_bf16_f32 %0, %1, %2" : "=v"(r) : "v"(lo), "v"(hi)); return r; }
; __device__ __forceinline__ float bflo(unsigned w) { return __uint_as_float(w << 16); }
; __device__ __forceinline__ float bfhi(unsigned w) { return __uint_as_float(w & 0xffff0000u); }
; __device__ __forceinline__ int otid() { int t = threadIdx.x; asm volatile("" : "+v"(t)); return t; }
; __device__ void attn_item(const Params& p, int l, int item, LAS unsigned char* lds) {
;     const int tid = otid(), wid = __builtin_amdgcn_readfirstlane(tid >> 6), lane = tid & 63, l31 = lane & 31, hi = lane >> 5;
;     const bool isctx = item >= 512;
;     int b, n, h, hb, qrow0;
;     if (!isctx) { b = item >> 7; n = (item >> 2) & 31; h = (item >> 1) & 1; hb = item & 1; qrow0 = b * 4096 + n * 128; }
;     else { const int j = item - 512; b = j >> 3; n = (j >> 2) & 1; h = (j >> 1) & 1; hb = j & 1; qrow0 = NL + b * 256 + n * 128; }
;     const bf16_t* P1 = (const bf16_t*)(p.ws + OFF_P1);
;     bf16_t* AM = (bf16_t*)(p.ws + OFF_AM);
;     LAS unsigned char* Kl = lds; LAS unsigned char* Vt = lds + 128 * KPITCH;
;     const int g = wid >> 1, head = 4 * h + g, qq = 64 * hb + 32 * (wid & 1) + l31;
;     bf16x8 qf[4];
; #pragma unroll
;     for (int ks = 0; ks < 4; ++ks) {
;         const u32x4 w = *(const u32x4*)(P1 + (size_t)(qrow0 + qq) * P1LD + 256 + head * 64 + 16 * ks + 8 * hi);
;         u32x4 o; o.x = pk2(bflo(w.x) * 0.125f, bfhi(w.x) * 0.125f); o.y = pk2(bflo(w.y) * 0.125f, bfhi(w.y) * 0.125f);
;         o.z = pk2(bflo(w.z) * 0.125f, bfhi(w.z) * 0.125f); o.w = pk2(bflo(w.w) * 0.125f, bfhi(w.w) * 0.125f);
;         qf[ks] = __builtin_bit_cast(bf16x8, o);
;     }
;     f32x16 ot[2];
;     float mrun = -1e30f, lrun = 0.f;
; #pragma unroll
;     for (int dt = 0; dt < 2; ++dt)
; #pragma unroll
;         for (int r = 0; r < 16; ++r) ot[dt][r] = 0.f;
.LBB0_181:
	s_bfe_u32 s4, s29, 0x10001
	s_ashr_i32 s15, s7, 1
	s_lshl_b32 s5, s4, 2
	s_add_i32 s15, s15, s5
	s_lshl_b32 s5, s29, 6
	s_lshl_b32 s7, s7, 5
	s_and_b32 s5, s5, 64
	s_and_b32 s7, s7, 32
	v_and_b32_e32 v5, 31, v2
	s_or_b32 s5, s5, s7
	v_or_b32_e32 v146, s5, v5
	v_add_u32_e32 v0, s6, v146
	v_mad_i64_i32 v[140:141], s[20:21], v0, s38, 0
	v_mad_i64_i32 v[0:1], s[20:21], v0, s38, v[136:137]
	s_lshl_b32 s20, s15, 6
	v_bfe_u32 v6, v2, 5, 1
	s_ashr_i32 s21, s20, 31
	v_lshl_add_u64 v[0:1], s[20:21], 1, v[0:1]
	v_lshlrev_b32_e32 v96, 4, v6
	v_lshl_add_u64 v[0:1], v[0:1], 0, v[96:97]
	global_load_dwordx4 v[10:13], v[0:1], off offset:512
	global_load_dwordx4 v[32:35], v[0:1], off offset:544
	global_load_dwordx4 v[36:39], v[0:1], off offset:576
	global_load_dwordx4 v[40:43], v[0:1], off offset:608
	s_lshl_b32 s5, s34, 7
	s_add_i32 s31, s2, 0x3e80
	s_add_i32 s2, s31, s5
	s_and_b64 s[22:23], s[18:19], exec
	v_and_b32_e32 v7, 63, v2
	s_cselect_b32 s7, s6, s2
	s_lshl_b32 s2, s4, 7
	v_ashrrev_i32_e32 v147, 3, v2
	v_lshlrev_b32_e32 v149, 1, v7
	v_lshlrev_b32_e32 v8, 3, v6
	v_lshlrev_b32_e32 v7, 2, v7
	s_cmp_eq_u32 s11, 31
	v_mov_b32_e32 v223, 0
	s_cselect_b64 s[22:23], -1, 0
	s_add_i32 s33, s6, 0xffffff80
	v_mov_b32_e32 v224, 0xf149f2ca
	v_mov_b32_e32 v14, v223
	v_mov_b32_e32 v15, v223
	v_mov_b32_e32 v16, 0
	v_mov_b32_e32 v17, v223
	v_mov_b32_e32 v18, v223
	v_mov_b32_e32 v19, v223
	v_mov_b32_e32 v20, v223
	v_mov_b32_e32 v21, v223
	v_mov_b32_e32 v22, v223
	v_mov_b32_e32 v23, v223
	v_mov_b32_e32 v24, v223
	v_mov_b32_e32 v25, v223
	v_mov_b32_e32 v26, v223
	v_mov_b32_e32 v27, v223
	v_mov_b32_e32 v28, v223
	v_mov_b32_e32 v29, v223
	v_mov_b32_e32 v30, v223
	v_mov_b32_e32 v31, v223
	s_waitcnt vmcnt(3) lgkmcnt(0)
	v_lshlrev_b32_e32 v3, 16, v10
	v_and_b32_e32 v9, 0xffff0000, v10
	v_mul_f32_e32 v3, 0x3e000000, v3
	v_mul_f32_e32 v9, 0x3e000000, v9
	v_cvt_pk_bf16_f32 v98, v3, v9
	v_lshlrev_b32_e32 v3, 16, v11
	v_and_b32_e32 v9, 0xffff0000, v11
	v_mul_f32_e32 v3, 0x3e000000, v3
	v_mul_f32_e32 v9, 0x3e000000, v9
	v_cvt_pk_bf16_f32 v99, v3, v9
	v_lshlrev_b32_e32 v3, 16, v12
	v_and_b32_e32 v9, 0xffff0000, v12
	v_mul_f32_e32 v3, 0x3e000000, v3
	v_mul_f32_e32 v9, 0x3e000000, v9
	v_cvt_pk_bf16_f32 v100, v3, v9
	v_lshlrev_b32_e32 v3, 16, v13
	v_and_b32_e32 v9, 0xffff0000, v13
	v_mul_f32_e32 v3, 0x3e000000, v3
	v_mul_f32_e32 v9, 0x3e000000, v9
	v_cvt_pk_bf16_f32 v101, v3, v9
	s_waitcnt vmcnt(2)
	v_lshlrev_b32_e32 v3, 16, v32
	v_and_b32_e32 v9, 0xffff0000, v32
	v_mul_f32_e32 v3, 0x3e000000, v3
	v_mul_f32_e32 v9, 0x3e000000, v9
	v_cvt_pk_bf16_f32 v102, v3, v9
	v_lshlrev_b32_e32 v3, 16, v33
	v_and_b32_e32 v9, 0xffff0000, v33
	v_mul_f32_e32 v3, 0x3e000000, v3
	v_mul_f32_e32 v9, 0x3e000000, v9
	v_cvt_pk_bf16_f32 v103, v3, v9
	v_lshlrev_b32_e32 v3, 16, v34
	v_and_b32_e32 v9, 0xffff0000, v34
	v_mul_f32_e32 v3, 0x3e000000, v3
	v_mul_f32_e32 v9, 0x3e000000, v9
	v_cvt_pk_bf16_f32 v104, v3, v9
	v_lshlrev_b32_e32 v3, 16, v35
	v_and_b32_e32 v9, 0xffff0000, v35
	v_mul_f32_e32 v3, 0x3e000000, v3
	v_mul_f32_e32 v9, 0x3e000000, v9
	v_cvt_pk_bf16_f32 v105, v3, v9
	s_waitcnt vmcnt(1)
	v_lshlrev_b32_e32 v3, 16, v36
	v_and_b32_e32 v9, 0xffff0000, v36
	v_mul_f32_e32 v3, 0x3e000000, v3
	v_mul_f32_e32 v9, 0x3e000000, v9
	v_cvt_pk_bf16_f32 v106, v3, v9
	v_lshlrev_b32_e32 v3, 16, v37
	v_and_b32_e32 v9, 0xffff0000, v37
	v_mul_f32_e32 v3, 0x3e000000, v3
	v_mul_f32_e32 v9, 0x3e000000, v9
	v_cvt_pk_bf16_f32 v107, v3, v9
	v_lshlrev_b32_e32 v3, 16, v38
	v_and_b32_e32 v9, 0xffff0000, v38
	v_mul_f32_e32 v3, 0x3e000000, v3
	v_mul_f32_e32 v9, 0x3e000000, v9
	v_cvt_pk_bf16_f32 v108, v3, v9
	v_lshlrev_b32_e32 v3, 16, v39
	v_and_b32_e32 v9, 0xffff0000, v39
	v_mul_f32_e32 v3, 0x3e000000, v3
	v_mul_f32_e32 v9, 0x3e000000, v9
	v_cvt_pk_bf16_f32 v109, v3, v9
	v_lshlrev_b32_e32 v3, 4, v2
	v_add_u32_e32 v2, 0x200, v2
	v_ashrrev_i32_e32 v148, 3, v2
	v_add_u32_e32 v2, s7, v148
	v_add_u32_e32 v9, s7, v149
	s_waitcnt vmcnt(0)
; #define GAS __attribute__((address_space(1)))
; __device__ void attn_item(const Params& p, int l, int item, LAS unsigned char* lds) {
;     ...
;     GAS const bf16_t* P1g = (GAS const bf16_t*)(unsigned long long)P1;
;     const int pr = tid & 63, vslab = tid >> 6;
;     ...
;     u32x4 kw[2], w0, w1;
;     {
;         const int kb0 = ATT_KBASE(isctx ? 3 : 0);
; #pragma unroll
;         for (int i = 0; i < 2; ++i) { const int q = tid + 512 * i, key = q >> 3, slab = q & 7;
;             kw[i] = *(GAS const u32x4*)(P1g + (size_t)(kb0 + key) * P1LD + 64 * h + 8 * slab); }
;         w0 = *(GAS const u32x4*)(P1g + (size_t)(kb0 + 2 * pr) * P1LD + 128 + 64 * h + 8 * vslab);
;         w1 = *(GAS const u32x4*)(P1g + (size_t)(kb0 + 2 * pr + 1) * P1LD + 128 + 64 * h + 8 * vslab);
;     }
;     ...
; #pragma unroll
;             for (int kt = 0; kt < 4; ++kt)
; #pragma unroll
;                 for (int r = 0; r < 16; ++r) {
;                     const int kk = 32 * kt + 8 * (r >> 2) + 4 * hi + (r & 3);
;                     st[kt][r] = (kk >= klo && kk <= khi) ? st[kt][r] : -1e30f;
;                 }
	v_lshlrev_b32_e32 v0, 16, v40
	v_and_b32_e32 v1, 0xffff0000, v40
	v_mul_f32_e32 v0, 0x3e000000, v0
	v_mul_f32_e32 v1, 0x3e000000, v1
	v_cvt_pk_bf16_f32 v110, v0, v1
	v_lshlrev_b32_e32 v0, 16, v41
	v_and_b32_e32 v1, 0xffff0000, v41
	v_mul_f32_e32 v0, 0x3e000000, v0
	v_mul_f32_e32 v1, 0x3e000000, v1
	v_cvt_pk_bf16_f32 v111, v0, v1
	v_lshlrev_b32_e32 v0, 16, v42
	v_and_b32_e32 v1, 0xffff0000, v42
	v_mul_f32_e32 v0, 0x3e000000, v0
	v_mul_f32_e32 v1, 0x3e000000, v1
	v_cvt_pk_bf16_f32 v112, v0, v1
	v_lshlrev_b32_e32 v0, 16, v43
	v_and_b32_e32 v1, 0xffff0000, v43
	v_mul_f32_e32 v0, 0x3e000000, v0
	v_mul_f32_e32 v1, 0x3e000000, v1
	v_cvt_pk_bf16_f32 v113, v0, v1
	v_lshl_add_u64 v[0:1], v[136:137], 0, s[2:3]
	v_and_b32_e32 v10, 0x70, v3
	v_mov_b32_e32 v11, v97
	v_lshl_add_u64 v[142:143], v[0:1], 0, v[10:11]
	v_add_u32_e32 v3, s7, v147
	v_mad_i64_i32 v[12:13], s[4:5], v3, s38, v[142:143]
	v_mad_i64_i32 v[2:3], s[4:5], v2, s38, v[142:143]
	global_load_dwordx4 v[114:117], v[12:13], off
	global_load_dwordx4 v[118:121], v[2:3], off
	v_mad_i64_i32 v[2:3], s[4:5], v9, s38, v[136:137]
	v_lshl_add_u64 v[12:13], v[2:3], 0, s[2:3]
	v_lshlrev_b32_e32 v2, 3, v4
	v_ashrrev_i32_e32 v3, 31, v2
	v_lshlrev_b64 v[2:3], 1, v[2:3]
	v_lshl_add_u64 v[12:13], v[12:13], 0, v[2:3]
	v_add_u32_e32 v9, 1, v9
	global_load_dwordx4 v[122:125], v[12:13], off offset:256
	v_mad_i64_i32 v[12:13], s[4:5], v9, s38, v[136:137]
	v_lshl_add_u64 v[12:13], v[12:13], 0, s[2:3]
	v_lshl_add_u64 v[12:13], v[12:13], 0, v[2:3]
	global_load_dwordx4 v[126:129], v[12:13], off offset:256
	s_movk_i32 s2, 0x880
	v_add_u32_e32 v9, 0, v10
	v_mul_lo_u32 v4, v4, s2
	v_add_u32_e32 v10, 0, v96
	s_movk_i32 s4, 0x90
	v_add_u32_e32 v4, 0, v4
	v_lshlrev_b32_e32 v96, 2, v6
	v_sub_u32_e32 v6, v10, v8
	v_mul_u32_u24_e32 v8, 0x110, v5
	v_mul_lo_u32 v11, v147, s4
	v_mul_lo_u32 v12, v148, s4
	v_mul_u32_u24_e32 v5, 0x90, v5
	s_add_i32 s2, s6, 0x80
	v_or_b32_e32 v150, 1, v96
	v_or_b32_e32 v151, 2, v96
	v_or_b32_e32 v152, 3, v96
	v_or_b32_e32 v153, 8, v96
	v_or_b32_e32 v154, 9, v96
	v_or_b32_e32 v155, 10, v96
	v_or_b32_e32 v156, 11, v96
	v_or_b32_e32 v157, 16, v96
	v_or_b32_e32 v158, 17, v96
	v_or_b32_e32 v159, 18, v96
	v_or_b32_e32 v160, 19, v96
	v_or_b32_e32 v161, 24, v96
	v_or_b32_e32 v162, 25, v96
	v_or_b32_e32 v163, 26, v96
	v_or_b32_e32 v164, 27, v96
	v_or_b32_e32 v165, 32, v96
	v_or_b32_e32 v166, 33, v96
	v_or_b32_e32 v167, 34, v96
	v_or_b32_e32 v168, 35, v96
	v_or_b32_e32 v169, 40, v96
	v_or_b32_e32 v170, 41, v96
	v_or_b32_e32 v171, 42, v96
	v_or_b32_e32 v172, 43, v96
	v_or_b32_e32 v173, 48, v96
	v_or_b32_e32 v174, 49, v96
	v_or_b32_e32 v175, 50, v96
	v_or_b32_e32 v176, 51, v96
	v_or_b32_e32 v177, 56, v96
	v_or_b32_e32 v178, 57, v96
	v_or_b32_e32 v179, 58, v96
	v_or_b32_e32 v180, 59, v96
	v_or_b32_e32 v181, 64, v96
	v_or_b32_e32 v182, 0x41, v96
	v_or_b32_e32 v183, 0x42, v96
	v_or_b32_e32 v184, 0x43, v96
	v_or_b32_e32 v185, 0x48, v96
	v_or_b32_e32 v186, 0x49, v96
	v_or_b32_e32 v187, 0x4a, v96
	v_or_b32_e32 v188, 0x4b, v96
	v_or_b32_e32 v189, 0x50, v96
	v_or_b32_e32 v190, 0x51, v96
	v_or_b32_e32 v191, 0x52, v96
	v_or_b32_e32 v192, 0x53, v96
	v_or_b32_e32 v193, 0x58, v96
	v_or_b32_e32 v194, 0x59, v96
	v_or_b32_e32 v195, 0x5a, v96
	v_or_b32_e32 v196, 0x5b, v96
	v_or_b32_e32 v197, 0x60, v96
	v_or_b32_e32 v198, 0x61, v96
	v_or_b32_e32 v199, 0x62, v96
	v_or_b32_e32 v200, 0x63, v96
	v_or_b32_e32 v201, 0x68, v96
	v_or_b32_e32 v202, 0x69, v96
	v_or_b32_e32 v203, 0x6a, v96
	v_or_b32_e32 v204, 0x6b, v96
	v_or_b32_e32 v205, 0x70, v96
	v_or_b32_e32 v206, 0x71, v96
	v_or_b32_e32 v207, 0x72, v96
	v_or_b32_e32 v208, 0x73, v96
	v_or_b32_e32 v209, 0x78, v96
	v_or_b32_e32 v211, 0x79, v96
	v_or_b32_e32 v216, 0x7a, v96
	v_or_b32_e32 v217, 0x7b, v96
	v_lshl_add_u64 v[144:145], v[0:1], 0, v[2:3]
	v_add_u32_e32 v218, v9, v11
	v_add_u32_e32 v219, v9, v12
	v_add_u32_e32 v220, v4, v7
	v_add_u32_e32 v221, v10, v5
	v_add_u32_e32 v222, v6, v8
	v_mov_b32_e32 v0, 0
	v_mov_b32_e32 v1, v223
	v_mov_b32_e32 v2, v223
	v_mov_b32_e32 v3, v223
	v_mov_b32_e32 v4, v223
	v_mov_b32_e32 v5, v223
	v_mov_b32_e32 v6, v223
	v_mov_b32_e32 v7, v223
	v_mov_b32_e32 v8, v223
	v_mov_b32_e32 v9, v223
	v_mov_b32_e32 v10, v223
	v_mov_b32_e32 v11, v223
	v_mov_b32_e32 v12, v223
	v_mov_b32_e32 v13, v223

; #define LAS __attribute__((address_space(3)))
; __device__ void attn_item(const Params& p, int l, int item, LAS unsigned char* lds) {
;     ...
; #pragma unroll
;         for (int kt = 0; kt < 4; ++kt) {
; #pragma unroll
;             for (int r = 0; r < 16; ++r) st[kt][r] = 0.f;
; #pragma unroll
;             for (int ks = 0; ks < 4; ++ks) {
;                 const bf16x8 kf = *(const LAS bf16x8*)(Kl + (32 * kt + l31) * KPITCH + 32 * ks + 16 * hi);
;                 st[kt] = __builtin_amdgcn_mfma_f32_32x32x16_bf16(kf, qf[ks], st[kt], 0, 0, 0);
;             }
;         }
;         __builtin_amdgcn_sched_barrier(0);
;         float mx = -1e30f;
;         if (mask) {
;             int klo = (mask == 1) ? qq : -1, khi = (mask == 2) ? qq : 1000;
;             asm volatile("" : "+v"(klo), "+v"(khi));
; #pragma unroll
;             for (int kt = 0; kt < 4; ++kt)
; #pragma unroll
;                 for (int r = 0; r < 16; ++r) {
;                     const int kk = 32 * kt + 8 * (r >> 2) + 4 * hi + (r & 3);
;                     st[kt][r] = (kk >= klo && kk <= khi) ? st[kt][r] : -1e30f;
;                 }
;         }
.LBB0_192:
	ds_read_b128 v[32:35], v221
	ds_read_b128 v[36:39], v221 offset:32
	s_waitcnt lgkmcnt(1)
	v_mfma_f32_32x32x16_bf16 v[80:95], v[32:35], v[98:101], 0
	ds_read_b128 v[32:35], v221 offset:64
	ds_read_b128 v[226:229], v221 offset:13856
	s_waitcnt lgkmcnt(2)
	v_mfma_f32_32x32x16_bf16 v[80:95], v[36:39], v[102:105], v[80:95]
	s_waitcnt lgkmcnt(1)
	v_mfma_f32_32x32x16_bf16 v[80:95], v[32:35], v[106:109], v[80:95]
	ds_read_b128 v[32:35], v221 offset:96
	s_waitcnt lgkmcnt(0)
	v_mfma_f32_32x32x16_bf16 v[80:95], v[32:35], v[110:113], v[80:95]
	ds_read_b128 v[32:35], v221 offset:4608
	s_waitcnt lgkmcnt(0)
	v_mfma_f32_32x32x16_bf16 v[64:79], v[32:35], v[98:101], 0
	ds_read_b128 v[32:35], v221 offset:4640
	s_waitcnt lgkmcnt(0)
	v_mfma_f32_32x32x16_bf16 v[64:79], v[32:35], v[102:105], v[64:79]
	ds_read_b128 v[32:35], v221 offset:4672
	s_waitcnt lgkmcnt(0)
	v_mfma_f32_32x32x16_bf16 v[64:79], v[32:35], v[106:109], v[64:79]
	ds_read_b128 v[32:35], v221 offset:4704
	s_waitcnt lgkmcnt(0)
	v_mfma_f32_32x32x16_bf16 v[64:79], v[32:35], v[110:113], v[64:79]
	ds_read_b128 v[32:35], v221 offset:9216
	s_waitcnt lgkmcnt(0)
	v_mfma_f32_32x32x16_bf16 v[48:63], v[32:35], v[98:101], 0
	ds_read_b128 v[32:35], v221 offset:9248
	s_waitcnt lgkmcnt(0)
	v_mfma_f32_32x32x16_bf16 v[48:63], v[32:35], v[102:105], v[48:63]
	ds_read_b128 v[32:35], v221 offset:9280
	s_waitcnt lgkmcnt(0)
	v_mfma_f32_32x32x16_bf16 v[48:63], v[32:35], v[106:109], v[48:63]
	ds_read_b128 v[32:35], v221 offset:9312
	s_waitcnt lgkmcnt(0)
	v_mfma_f32_32x32x16_bf16 v[48:63], v[32:35], v[110:113], v[48:63]
	ds_read_b128 v[32:35], v221 offset:13824
	s_waitcnt lgkmcnt(0)
	v_mfma_f32_32x32x16_bf16 v[32:47], v[32:35], v[98:101], 0
	v_mfma_f32_32x32x16_bf16 v[32:47], v[226:229], v[102:105], v[32:47]
	ds_read_b128 v[226:229], v221 offset:13888
	s_waitcnt lgkmcnt(0)
	v_mfma_f32_32x32x16_bf16 v[32:47], v[226:229], v[106:109], v[32:47]
	ds_read_b128 v[226:229], v221 offset:13920
	s_waitcnt lgkmcnt(0)
	v_mfma_f32_32x32x16_bf16 v[32:47], v[226:229], v[110:113], v[32:47]
	s_add_i32 s4, s34, -3
	s_cmp_lt_u32 s4, -2
	s_cbranch_scc1 .LBB0_194
	s_cmp_eq_u32 s34, 1
	s_cbranch_scc0 .Lmy_mask2
	v_cmp_lt_i32_e32 vcc, v96, v146
	v_cmp_lt_i32_e64 s[40:41], v150, v146
	v_cmp_lt_i32_e64 s[42:43], v151, v146
	v_cndmask_b32_e32 v80, v80, v242, vcc
	v_cmp_lt_i32_e32 vcc, v152, v146
	v_cndmask_b32_e64 v81, v81, v242, s[40:41]
	v_cmp_lt_i32_e64 s[40:41], v153, v146
	v_cndmask_b32_e64 v82, v82, v242, s[42:43]
	v_cmp_lt_i32_e64 s[42:43], v154, v146
	v_cndmask_b32_e32 v83, v83, v242, vcc
	v_cmp_lt_i32_e32 vcc, v155, v146
	v_cndmask_b32_e64 v84, v84, v242, s[40:41]
	v_cmp_lt_i32_e64 s[40:41], v156, v146
	v_cndmask_b32_e64 v85, v85, v242, s[42:43]
	v_cmp_lt_i32_e64 s[42:43], v157, v146
	v_cndmask_b32_e32 v86, v86, v242, vcc
	v_cmp_lt_i32_e32 vcc, v158, v146
	v_cndmask_b32_e64 v87, v87, v242, s[40:41]
	v_cmp_lt_i32_e64 s[40:41], v159, v146
	v_cndmask_b32_e64 v88, v88, v242, s[42:43]
	v_cmp_lt_i32_e64 s[42:43], v160, v146
	v_cndmask_b32_e32 v89, v89, v242, vcc
	v_cmp_lt_i32_e32 vcc, v161, v146
	v_cndmask_b32_e64 v90, v90, v242, s[40:41]
	v_cmp_lt_i32_e64 s[40:41], v162, v146
	v_cndmask_b32_e64 v91, v91, v242, s[42:43]
	v_cmp_lt_i32_e64 s[42:43], v163, v146
	v_cndmask_b32_e32 v92, v92, v242, vcc
	v_cmp_lt_i32_e32 vcc, v164, v146
	v_cndmask_b32_e64 v93, v93, v242, s[40:41]
	v_cmp_lt_i32_e64 s[40:41], v165, v146
	v_cndmask_b32_e64 v94, v94, v242, s[42:43]
	v_cmp_lt_i32_e64 s[42:43], v166, v146
	v_cndmask_b32_e32 v95, v95, v242, vcc
	v_cmp_lt_i32_e32 vcc, v167, v146
	v_cndmask_b32_e64 v64, v64, v242, s[40:41]
	v_cmp_lt_i32_e64 s[40:41], v168, v146
	v_cndmask_b32_e64 v65, v65, v242, s[42:43]
	v_cmp_lt_i32_e64 s[42:43], v169, v146
	v_cndmask_b32_e32 v66, v66, v242, vcc
	v_cmp_lt_i32_e32 vcc, v170, v146
	v_cndmask_b32_e64 v67, v67, v242, s[40:41]
	v_cmp_lt_i32_e64 s[40:41], v171, v146
	v_cndmask_b32_e64 v68, v68, v242, s[42:43]
	v_cmp_lt_i32_e64 s[42:43], v172, v146
	v_cndmask_b32_e32 v69, v69, v242, vcc
	v_cmp_lt_i32_e32 vcc, v173, v146
	v_cndmask_b32_e64 v70, v70, v242, s[40:41]
	v_cmp_lt_i32_e64 s[40:41], v174, v146
	v_cndmask_b32_e64 v71, v71, v242, s[42:43]
	v_cmp_lt_i32_e64 s[42:43], v175, v146
	v_cndmask_b32_e32 v72, v72, v242, vcc
	v_cmp_lt_i32_e32 vcc, v176, v146
	v_cndmask_b32_e64 v73, v73, v242, s[40:41]
	v_cmp_lt_i32_e64 s[40:41], v177, v146
	v_cndmask_b32_e64 v74, v74, v242, s[42:43]
	v_cmp_lt_i32_e64 s[42:43], v178, v146
	v_cndmask_b32_e32 v75, v75, v242, vcc
	v_cmp_lt_i32_e32 vcc, v179, v146
	v_cndmask_b32_e64 v76, v76, v242, s[40:41]
	v_cmp_lt_i32_e64 s[40:41], v180, v146
	v_cndmask_b32_e64 v77, v77, v242, s[42:43]
	v_cmp_lt_i32_e64 s[42:43], v181, v146
	v_cndmask_b32_e32 v78, v78, v242, vcc
	v_cmp_lt_i32_e32 vcc, v182, v146
	v_cndmask_b32_e64 v79, v79, v242, s[40:41]
	v_cmp_lt_i32_e64 s[40:41], v183, v146
	v_cndmask_b32_e64 v48, v48, v242, s[42:43]
	v_cmp_lt_i32_e64 s[42:43], v184, v146
	v_cndmask_b32_e32 v49, v49, v242, vcc
	v_cmp_lt_i32_e32 vcc, v185, v146
	v_cndmask_b32_e64 v50, v50, v242, s[40:41]
	v_cmp_lt_i32_e64 s[40:41], v186, v146
	v_cndmask_b32_e64 v51, v51, v242, s[42:43]
	v_cmp_lt_i32_e64 s[42:43], v187, v146
	v_cndmask_b32_e32 v52, v52, v242, vcc
	v_cmp_lt_i32_e32 vcc, v188, v146
	v_cndmask_b32_e64 v53, v53, v242, s[40:41]
	v_cmp_lt_i32_e64 s[40:41], v189, v146
	v_cndmask_b32_e64 v54, v54, v242, s[42:43]
	v_cmp_lt_i32_e64 s[42:43], v190, v146
	v_cndmask_b32_e32 v55, v55, v242, vcc
	v_cmp_lt_i32_e32 vcc, v191, v146
	v_cndmask_b32_e64 v56, v56, v242, s[40:41]
	v_cmp_lt_i32_e64 s[40:41], v192, v146
	v_cndmask_b32_e64 v57, v57, v242, s[42:43]
	v_cmp_lt_i32_e64 s[42:43], v193, v146
	v_cndmask_b32_e32 v58, v58, v242, vcc
; __device__ void attn_item(const Params& p, int l, int item, LAS unsigned char* lds) {
;     ...
;         if (mask) {
;             int klo = (mask == 1) ? qq : -1, khi = (mask == 2) ? qq : 1000;
;             asm volatile("" : "+v"(klo), "+v"(khi));
; #pragma unroll
;             for (int kt = 0; kt < 4; ++kt)
; #pragma unroll
;                 for (int r = 0; r < 16; ++r) {
;                     const int kk = 32 * kt + 8 * (r >> 2) + 4 * hi + (r & 3);
;                     st[kt][r] = (kk >= klo && kk <= khi) ? st[kt][r] : -1e30f;
;                 }
;         }
	v_cmp_lt_i32_e32 vcc, v194, v146
	v_cndmask_b32_e64 v59, v59, v242, s[40:41]
	v_cmp_lt_i32_e64 s[40:41], v195, v146
	v_cndmask_b32_e64 v60, v60, v242, s[42:43]
	v_cmp_lt_i32_e64 s[42:43], v196, v146
	v_cndmask_b32_e32 v61, v61, v242, vcc
	v_cmp_lt_i32_e32 vcc, v197, v146
	v_cndmask_b32_e64 v62, v62, v242, s[40:41]
	v_cmp_lt_i32_e64 s[40:41], v198, v146
	v_cndmask_b32_e64 v63, v63, v242, s[42:43]
	v_cmp_lt_i32_e64 s[42:43], v199, v146
	v_cndmask_b32_e32 v32, v32, v242, vcc
	v_cmp_lt_i32_e32 vcc, v200, v146
	v_cndmask_b32_e64 v33, v33, v242, s[40:41]
	v_cmp_lt_i32_e64 s[40:41], v201, v146
	v_cndmask_b32_e64 v34, v34, v242, s[42:43]
	v_cmp_lt_i32_e64 s[42:43], v202, v146
	v_cndmask_b32_e32 v35, v35, v242, vcc
	v_cmp_lt_i32_e32 vcc, v203, v146
	v_cndmask_b32_e64 v36, v36, v242, s[40:41]
	v_cmp_lt_i32_e64 s[40:41], v204, v146
	v_cndmask_b32_e64 v37, v37, v242, s[42:43]
	v_cmp_lt_i32_e64 s[42:43], v205, v146
	v_cndmask_b32_e32 v38, v38, v242, vcc
	v_cmp_lt_i32_e32 vcc, v206, v146
	v_cndmask_b32_e64 v39, v39, v242, s[40:41]
	v_cmp_lt_i32_e64 s[40:41], v207, v146
	v_cndmask_b32_e64 v40, v40, v242, s[42:43]
	v_cmp_lt_i32_e64 s[42:43], v208, v146
	v_cndmask_b32_e32 v41, v41, v242, vcc
	v_cmp_lt_i32_e32 vcc, v209, v146
	v_cndmask_b32_e64 v42, v42, v242, s[40:41]
	v_cmp_lt_i32_e64 s[40:41], v211, v146
	v_cndmask_b32_e64 v43, v43, v242, s[42:43]
	v_cmp_lt_i32_e64 s[42:43], v216, v146
	v_cndmask_b32_e32 v44, v44, v242, vcc
	v_cmp_lt_i32_e32 vcc, v217, v146
	v_cndmask_b32_e64 v45, v45, v242, s[40:41]
	v_cndmask_b32_e64 v46, v46, v242, s[42:43]
	v_cndmask_b32_e32 v47, v47, v242, vcc
	s_branch .LBB0_194
.Lmy_mask2:
	v_cmp_gt_i32_e32 vcc, v96, v146
	v_cmp_gt_i32_e64 s[40:41], v150, v146
	v_cmp_gt_i32_e64 s[42:43], v151, v146
	v_cndmask_b32_e32 v80, v80, v242, vcc
	v_cmp_gt_i32_e32 vcc, v152, v146
	v_cndmask_b32_e64 v81, v81, v242, s[40:41]
	v_cmp_gt_i32_e64 s[40:41], v153, v146
	v_cndmask_b32_e64 v82, v82, v242, s[42:43]
	v_cmp_gt_i32_e64 s[42:43], v154, v146
	v_cndmask_b32_e32 v83, v83, v242, vcc
	v_cmp_gt_i32_e32 vcc, v155, v146
	v_cndmask_b32_e64 v84, v84, v242, s[40:41]
	v_cmp_gt_i32_e64 s[40:41], v156, v146
	v_cndmask_b32_e64 v85, v85, v242, s[42:43]
	v_cmp_gt_i32_e64 s[42:43], v157, v146
	v_cndmask_b32_e32 v86, v86, v242, vcc
	v_cmp_gt_i32_e32 vcc, v158, v146
	v_cndmask_b32_e64 v87, v87, v242, s[40:41]
	v_cmp_gt_i32_e64 s[40:41], v159, v146
	v_cndmask_b32_e64 v88, v88, v242, s[42:43]
	v_cmp_gt_i32_e64 s[42:43], v160, v146
	v_cndmask_b32_e32 v89, v89, v242, vcc
	v_cmp_gt_i32_e32 vcc, v161, v146
	v_cndmask_b32_e64 v90, v90, v242, s[40:41]
	v_cmp_gt_i32_e64 s[40:41], v162, v146
	v_cndmask_b32_e64 v91, v91, v242, s[42:43]
	v_cmp_gt_i32_e64 s[42:43], v163, v146
	v_cndmask_b32_e32 v92, v92, v242, vcc
	v_cmp_gt_i32_e32 vcc, v164, v146
	v_cndmask_b32_e64 v93, v93, v242, s[40:41]
	v_cmp_gt_i32_e64 s[40:41], v165, v146
	v_cndmask_b32_e64 v94, v94, v242, s[42:43]
	v_cmp_gt_i32_e64 s[42:43], v166, v146
	v_cndmask_b32_e32 v95, v95, v242, vcc
	v_cmp_gt_i32_e32 vcc, v167, v146
	v_cndmask_b32_e64 v64, v64, v242, s[40:41]
	v_cmp_gt_i32_e64 s[40:41], v168, v146
	v_cndmask_b32_e64 v65, v65, v242, s[42:43]
	v_cmp_gt_i32_e64 s[42:43], v169, v146
	v_cndmask_b32_e32 v66, v66, v242, vcc
	v_cmp_gt_i32_e32 vcc, v170, v146
	v_cndmask_b32_e64 v67, v67, v242, s[40:41]
	v_cmp_gt_i32_e64 s[40:41], v171, v146
	v_cndmask_b32_e64 v68, v68, v242, s[42:43]
	v_cmp_gt_i32_e64 s[42:43], v172, v146
	v_cndmask_b32_e32 v69, v69, v242, vcc
	v_cmp_gt_i32_e32 vcc, v173, v146
	v_cndmask_b32_e64 v70, v70, v242, s[40:41]
	v_cmp_gt_i32_e64 s[40:41], v174, v146
	v_cndmask_b32_e64 v71, v71, v242, s[42:43]
	v_cmp_gt_i32_e64 s[42:43], v175, v146
	v_cndmask_b32_e32 v72, v72, v242, vcc
	v_cmp_gt_i32_e32 vcc, v176, v146
	v_cndmask_b32_e64 v73, v73, v242, s[40:41]
	v_cmp_gt_i32_e64 s[40:41], v177, v146
	v_cndmask_b32_e64 v74, v74, v242, s[42:43]
	v_cmp_gt_i32_e64 s[42:43], v178, v146
	v_cndmask_b32_e32 v75, v75, v242, vcc
	v_cmp_gt_i32_e32 vcc, v179, v146
	v_cndmask_b32_e64 v76, v76, v242, s[40:41]
	v_cmp_gt_i32_e64 s[40:41], v180, v146
	v_cndmask_b32_e64 v77, v77, v242, s[42:43]
	v_cmp_gt_i32_e64 s[42:43], v181, v146
	v_cndmask_b32_e32 v78, v78, v242, vcc
	v_cmp_gt_i32_e32 vcc, v182, v146
	v_cndmask_b32_e64 v79, v79, v242, s[40:41]
	v_cmp_gt_i32_e64 s[40:41], v183, v146
	v_cndmask_b32_e64 v48, v48, v242, s[42:43]
	v_cmp_gt_i32_e64 s[42:43], v184, v146
	v_cndmask_b32_e32 v49, v49, v242, vcc
	v_cmp_gt_i32_e32 vcc, v185, v146
	v_cndmask_b32_e64 v50, v50, v242, s[40:41]
	v_cmp_gt_i32_e64 s[40:41], v186, v146
	v_cndmask_b32_e64 v51, v51, v242, s[42:43]
	v_cmp_gt_i32_e64 s[42:43], v187, v146
	v_cndmask_b32_e32 v52, v52, v242, vcc
	v_cmp_gt_i32_e32 vcc, v188, v146
	v_cndmask_b32_e64 v53, v53, v242, s[40:41]
	v_cmp_gt_i32_e64 s[40:41], v189, v146
	v_cndmask_b32_e64 v54, v54, v242, s[42:43]
	v_cmp_gt_i32_e64 s[42:43], v190, v146
	v_cndmask_b32_e32 v55, v55, v242, vcc
	v_cmp_gt_i32_e32 vcc, v191, v146
	v_cndmask_b32_e64 v56, v56, v242, s[40:41]
	v_cmp_gt_i32_e64 s[40:41], v192, v146
	v_cndmask_b32_e64 v57, v57, v242, s[42:43]
	v_cmp_gt_i32_e64 s[42:43], v193, v146
	v_cndmask_b32_e32 v58, v58, v242, vcc
	v_cmp_gt_i32_e32 vcc, v194, v146
	v_cndmask_b32_e64 v59, v59, v242, s[40:41]
	v_cmp_gt_i32_e64 s[40:41], v195, v146
	v_cndmask_b32_e64 v60, v60, v242, s[42:43]
	v_cmp_gt_i32_e64 s[42:43], v196, v146
	v_cndmask_b32_e32 v61, v61, v242, vcc
	v_cmp_gt_i32_e32 vcc, v197, v146
	v_cndmask_b32_e64 v62, v62, v242, s[40:41]
	v_cmp_gt_i32_e64 s[40:41], v198, v146
	v_cndmask_b32_e64 v63, v63, v242, s[42:43]
	v_cmp_gt_i32_e64 s[42:43], v199, v146
	v_cndmask_b32_e32 v32, v32, v242, vcc
	v_cmp_gt_i32_e32 vcc, v200, v146
	v_cndmask_b32_e64 v33, v33, v242, s[40:41]
	v_cmp_gt_i32_e64 s[40:41], v201, v146
	v_cndmask_b32_e64 v34, v34, v242, s[42:43]
	v_cmp_gt_i32_e64 s[42:43], v202, v146
	v_cndmask_b32_e32 v35, v35, v242, vcc
	v_cmp_gt_i32_e32 vcc, v203, v146
	v_cndmask_b32_e64 v36, v36, v242, s[40:41]
	v_cmp_gt_i32_e64 s[40:41], v204, v146
	v_cndmask_b32_e64 v37, v37, v242, s[42:43]
	v_cmp_gt_i32_e64 s[42:43], v205, v146
	v_cndmask_b32_e32 v38, v38, v242, vcc
	v_cmp_gt_i32_e32 vcc, v206, v146
	v_cndmask_b32_e64 v39, v39, v242, s[40:41]
	v_cmp_gt_i32_e64 s[40:41], v207, v146
	v_cndmask_b32_e64 v40, v40, v242, s[42:43]
	v_cmp_gt_i32_e64 s[42:43], v208, v146
	v_cndmask_b32_e32 v41, v41, v242, vcc
	v_cmp_gt_i32_e32 vcc, v209, v146
	v_cndmask_b32_e64 v42, v42, v242, s[40:41]
	v_cmp_gt_i32_e64 s[40:41], v211, v146
	v_cndmask_b32_e64 v43, v43, v242, s[42:43]
	v_cmp_gt_i32_e64 s[42:43], v216, v146
	v_cndmask_b32_e32 v44, v44, v242, vcc
	v_cmp_gt_i32_e32 vcc, v217, v146
	v_cndmask_b32_e64 v45, v45, v242, s[40:41]
	v_cndmask_b32_e64 v46, v46, v242, s[42:43]
	v_cndmask_b32_e32 v47, v47, v242, vcc
